# static priority, other half: per-phase s_setprio flips deleted, one s_setprio 1 for waves 0-3 at kernel start
# speedup vs baseline: 1.0131x; 1.0131x over previous
_Z6mk_fwd4Args:
	s_load_dwordx2 s[70:71], s[0:1], 0xe0
	s_load_dword s50, s[0:1], 0xe8
	s_mov_b64 s[76:77], s[0:1]
	s_add_u32 s6, s76, 0xe0
	v_and_b32_e32 v204, 0x3ff, v0
	s_addc_u32 s7, s77, 0
	v_cmp_gt_u32_e32 vcc, 16, v204
	s_and_saveexec_b64 s[0:1], vcc
	v_lshl_add_u32 v1, v204, 2, 0
	v_add_u32_e32 v1, 0x20140, v1
	v_mov_b32_e32 v2, 0
	ds_write_b32 v1, v2
	s_or_b64 exec, exec, s[0:1]
	s_waitcnt lgkmcnt(0)
	s_barrier
	v_readfirstlane_b32 s3, v204
	s_lshr_b32 s3, s3, 8
	s_cmp_eq_u32 s3, 0
	s_cbranch_scc0 .Lprio_static_done
	s_setprio 1
